# speedup vs baseline: 1.0120x; 1.0041x over previous
; __device__ __forceinline__ unsigned short f2bf(float f) { return (unsigned short)(cvt_pk_bf16(f, 0.f) & 0xffffu); }
; __device__ __forceinline__ float log2_gamma(int h) { return log2f(1.0f - exp2f(-5.0f - (float)h)); }
; __device__ __forceinline__ void tile_load(bf16_t* dst, const bf16_t* src, size_t ld, int tid) {
; #pragma unroll
;     for (int i = 0; i < 4; ++i) { const int ch = tid + 512 * i, r = ch >> 4, c0 = (ch & 15) * 8;
;         *(u32x4*)(dst + r * TS + c0) = *(const u32x4*)(src + (size_t)r * ld + c0); }
; }
; template <bool SCALE> __device__ __forceinline__ void tile_load_t(bf16_t* dst, const bf16_t* src, size_t ld, float l2g, int tid) {
; #pragma unroll
;     for (int i = 0; i < 4; ++i) { const int ch = tid + 512 * i, r = ch >> 4, c0 = (ch & 15) * 8;
;         const u32x4 raw = *(const u32x4*)(src + (size_t)r * ld + c0);
;         float f[8]; unpack8(raw, f);
;         if (SCALE) { const float z = exp2f(l2g * (float)(127 - r));
; #pragma unroll
;             for (int j = 0; j < 8; ++j) f[j] *= z; }
; #pragma unroll
;         for (int j = 0; j < 8; ++j) dst[(c0 + j) * TS + r] = f2bf(f[j]); }
; }
; __device__ __forceinline__ void ret_stepC(const Params& p, unsigned char* smem, int u) {
;     ...
;     const bf16_t* proj = (const bf16_t*)(p.ws + WS_PROJ) + tok0 * INP;
;     bf16_t* qs = (bf16_t*)smem; bf16_t* ks = (bf16_t*)(smem + TILE_B); bf16_t* vT = (bf16_t*)(smem + 2 * TILE_B); bf16_t* rs = (bf16_t*)(smem + 3 * TILE_B);
;     const float l2g = log2_gamma(h);
;     tile_load(qs, proj + C_RQ + h * 128, INP, tid);
;     tile_load(ks, proj + C_RK + h * 128, INP, tid);
;     tile_load_t<false>(vT, proj + C_RV + h * 128, INP, 0.f, tid);
;     tile_load(rs, (const bf16_t*)(p.ws + WS_RT) + (size_t)u * 16384, 128, tid);
.LBB0_1722:
	s_and_b32 s4, s83, 0xffffe000
	s_and_b32 s5, s82, 0x1f80
	s_bfe_u32 s36, s88, 0x30006
	s_or_b32 s62, s4, s5
	s_mul_i32 s5, s62, 0x3600
	v_cvt_f32_ubyte0_e32 v0, s36
	s_mul_hi_i32 s4, s62, 0x3600
	s_add_u32 s60, s84, s5
	v_sub_f32_e32 v50, 0xc0a00000, v0
	s_addc_u32 s61, s85, s4
	v_cmp_gt_f32_e32 vcc, s65, v50
	v_mov_b32_e32 v1, v166
	s_and_b64 s[4:5], vcc, exec
	s_cselect_b32 s8, 0xffffffc0, 0
	s_lshl_b32 s4, s36, 8
	v_lshlrev_b32_e32 v0, 3, v1
	s_add_u32 s4, s60, s4
	v_and_b32_e32 v3, 0x78, v0
	s_addc_u32 s5, s61, 0
	v_lshlrev_b32_e32 v48, 1, v3
	v_lshl_add_u64 v[40:41], s[4:5], 0, v[48:49]
	v_add_u32_e32 v2, 0x200, v1
	v_add_u32_e32 v4, 0x400, v1
	v_add_u32_e32 v5, 0x600, v1
	v_ashrrev_i32_e32 v0, 4, v1
	v_ashrrev_i32_e32 v2, 4, v2
	v_ashrrev_i32_e32 v4, 4, v4
	v_ashrrev_i32_e32 v6, 4, v5
	v_lshl_add_u64 v[44:45], v[40:41], 0, s[38:39]
	v_mad_i64_i32 v[12:13], s[4:5], v0, s64, v[40:41]
	v_mad_i64_i32 v[20:21], s[4:5], v2, s64, v[40:41]
	v_mad_i64_i32 v[28:29], s[4:5], v4, s64, v[40:41]
	v_mad_i64_i32 v[36:37], s[4:5], v6, s64, v[40:41]
	v_mad_i64_i32 v[40:41], s[4:5], v0, s64, v[44:45]
	global_load_dwordx4 v[8:11], v[12:13], off
	s_nop 0
	global_load_dwordx4 v[12:15], v[12:13], off offset:2048
	s_nop 0
	global_load_dwordx4 v[16:19], v[20:21], off
	s_nop 0
	global_load_dwordx4 v[20:23], v[20:21], off offset:2048
	s_nop 0
	global_load_dwordx4 v[24:27], v[28:29], off
	s_nop 0
	global_load_dwordx4 v[28:31], v[28:29], off offset:2048
	s_nop 0
	global_load_dwordx4 v[32:35], v[36:37], off
	s_nop 0
	global_load_dwordx4 v[36:39], v[36:37], off offset:2048
	v_mov_b32_e32 v5, s77
	global_load_dwordx4 v[40:43], v[40:41], off
	v_mad_i64_i32 v[132:133], s[4:5], v2, s64, v[44:45]
	v_mad_i64_i32 v[134:135], s[4:5], v4, s64, v[44:45]
	v_mad_i64_i32 v[136:137], s[4:5], v6, s64, v[44:45]
	global_load_dwordx4 v[140:143], v[132:133], off
	global_load_dwordx4 v[144:147], v[134:135], off
	global_load_dwordx4 v[148:151], v[136:137], off
	v_mul_lo_u32 v54, v0, s74
	v_mul_lo_u32 v57, v2, s74
	v_mul_lo_u32 v58, v4, s74
	v_mul_lo_u32 v59, v6, s74
	v_mad_u32_u24 v52, v3, s74, v5
	v_add_u32_e32 v3, 0, v48
	v_add_u32_e32 v7, v3, v54
	v_add_u32_e32 v53, v3, v57
	v_add_u32_e32 v55, v3, v58
	v_add_u32_e32 v3, v3, v59
	v_lshl_add_u32 v5, v0, 1, v52
	v_mad_i64_i32 v[46:47], s[4:5], v2, s64, v[44:45]
	v_cndmask_b32_e32 v51, 0, v78, vcc
	s_waitcnt vmcnt(11)
	ds_write_b128 v7, v[8:11]
	s_waitcnt vmcnt(9)
	ds_write_b128 v53, v[16:19]
	s_waitcnt vmcnt(7)
	ds_write_b128 v55, v[24:27]
	s_waitcnt vmcnt(5)
	ds_write_b128 v3, v[32:35]
	ds_write_b128 v7, v[12:15] offset:34816
	ds_write_b128 v53, v[20:23] offset:34816
	ds_write_b128 v55, v[28:31] offset:34816
	s_waitcnt vmcnt(4)
	ds_write_b128 v3, v[36:39] offset:34816
	v_lshl_add_u32 v17, v4, 1, v52
	s_waitcnt vmcnt(3)
	v_lshlrev_b32_e32 v3, 16, v40
	v_cvt_pk_bf16_f32 v3, v3, v49
	v_and_b32_e32 v7, 0xffff0000, v40
	ds_write_b16 v5, v3
	v_cvt_pk_bf16_f32 v3, v7, v49
	v_lshlrev_b32_e32 v8, 16, v41
	ds_write_b16 v5, v3 offset:272
	v_cvt_pk_bf16_f32 v3, v8, v49
	v_and_b32_e32 v9, 0xffff0000, v41
	ds_write_b16 v5, v3 offset:544
	v_cvt_pk_bf16_f32 v3, v9, v49
	v_lshlrev_b32_e32 v10, 16, v42
	ds_write_b16 v5, v3 offset:816
	v_cvt_pk_bf16_f32 v3, v10, v49
	v_and_b32_e32 v11, 0xffff0000, v42
	ds_write_b16 v5, v3 offset:1088
	v_cvt_pk_bf16_f32 v3, v11, v49
	v_lshlrev_b32_e32 v12, 16, v43
	ds_write_b16 v5, v3 offset:1360
	v_cvt_pk_bf16_f32 v3, v12, v49
	v_and_b32_e32 v13, 0xffff0000, v43
	ds_write_b16 v5, v3 offset:1632
	v_cvt_pk_bf16_f32 v3, v13, v49
	ds_write_b16 v5, v3 offset:1904
	v_lshl_add_u32 v7, v2, 1, v52
	v_mad_i64_i32 v[12:13], s[4:5], v4, s64, v[44:45]
	v_and_b32_e32 v21, 15, v1
	v_bfe_u32 v53, v1, 6, 2
	v_bfe_u32 v55, v1, 4, 2
	v_lshl_add_u32 v27, v6, 1, v52
	v_lshlrev_b32_e32 v22, 5, v53
	v_lshlrev_b32_e32 v16, 4, v55
	v_add_u32_e32 v25, 0, v16
	v_add_u32_e32 v31, s78, v48
	v_add_u32_e32 v32, v31, v54
	v_add_u32_e32 v33, v31, v57
	v_add_u32_e32 v34, v31, v58
	v_add_u32_e32 v31, v31, v59
	s_waitcnt vmcnt(2)
	v_mov_b64_e32 v[8:9], v[140:141]
	v_mov_b64_e32 v[10:11], v[142:143]
	v_lshlrev_b32_e32 v3, 16, v8
	v_cvt_pk_bf16_f32 v3, v3, v49
	v_and_b32_e32 v5, 0xffff0000, v8
	ds_write_b16 v7, v3
	v_cvt_pk_bf16_f32 v3, v5, v49
	v_lshlrev_b32_e32 v8, 16, v9
	ds_write_b16 v7, v3 offset:272
	v_cvt_pk_bf16_f32 v3, v8, v49
	v_and_b32_e32 v9, 0xffff0000, v9
	ds_write_b16 v7, v3 offset:544
	v_cvt_pk_bf16_f32 v3, v9, v49
	v_lshlrev_b32_e32 v14, 16, v10
	ds_write_b16 v7, v3 offset:816
	v_cvt_pk_bf16_f32 v3, v14, v49
	v_and_b32_e32 v10, 0xffff0000, v10
	ds_write_b16 v7, v3 offset:1088
	v_cvt_pk_bf16_f32 v3, v10, v49
	v_lshlrev_b32_e32 v15, 16, v11
	v_and_b32_e32 v11, 0xffff0000, v11
	ds_write_b16 v7, v3 offset:1360
	v_cvt_pk_bf16_f32 v3, v15, v49
	ds_write_b16 v7, v3 offset:1632
	v_cvt_pk_bf16_f32 v3, v11, v49
	ds_write_b16 v7, v3 offset:1904
	v_mad_i64_i32 v[12:13], s[4:5], v6, s64, v[44:45]
	s_waitcnt vmcnt(1)
; __device__ __forceinline__ unsigned short f2bf(float f) { return (unsigned short)(cvt_pk_bf16(f, 0.f) & 0xffffu); }
; template <bool SCALE> __device__ __forceinline__ void tile_load_t(bf16_t* dst, const bf16_t* src, size_t ld, float l2g, int tid) {
; #pragma unroll
;     for (int i = 0; i < 4; ++i) { const int ch = tid + 512 * i, r = ch >> 4, c0 = (ch & 15) * 8;
;         const u32x4 raw = *(const u32x4*)(src + (size_t)r * ld + c0);
;         float f[8]; unpack8(raw, f);
;         if (SCALE) { const float z = exp2f(l2g * (float)(127 - r));
; #pragma unroll
;             for (int j = 0; j < 8; ++j) f[j] *= z; }
; #pragma unroll
;         for (int j = 0; j < 8; ++j) dst[(c0 + j) * TS + r] = f2bf(f[j]); }
; }
; __device__ __forceinline__ void ret_stepC(const Params& p, unsigned char* smem, int u) {
;     ...
;     tile_load(rs, (const bf16_t*)(p.ws + WS_RT) + (size_t)u * 16384, 128, tid);
;     __syncthreads();
;     f32x4 accP[4][2];
; #pragma unroll
;     for (int m = 0; m < 4; ++m) { accP[m][0] = (f32x4){0, 0, 0, 0}; accP[m][1] = (f32x4){0, 0, 0, 0}; }
;     tile_mma(accP, ks, wc * 32, qs, wr * 64, fr, fq);
;     __syncthreads();
; #pragma unroll
;     for (int m = 0; m < 4; ++m)
; #pragma unroll
;         for (int nn = 0; nn < 2; ++nn) {
;             const int c = wr * 64 + m * 16 + fr, c2 = wc * 32 + nn * 16 + fq * 4;
;             float pv[4];
; #pragma unroll
;             for (int j = 0; j < 4; ++j) { const int df = c - (c2 + j); pv[j] = df >= 0 ? accP[m][nn][j] * exp2f(l2g * (float)df) : 0.f; }
	v_mov_b64_e32 v[8:9], v[144:145]
	v_mov_b64_e32 v[10:11], v[146:147]
	v_lshlrev_b32_e32 v3, 16, v8
	v_cvt_pk_bf16_f32 v3, v3, v49
	v_and_b32_e32 v5, 0xffff0000, v8
	ds_write_b16 v17, v3
	v_cvt_pk_bf16_f32 v3, v5, v49
	v_lshlrev_b32_e32 v7, 16, v9
	ds_write_b16 v17, v3 offset:272
	v_cvt_pk_bf16_f32 v3, v7, v49
	v_and_b32_e32 v8, 0xffff0000, v9
	ds_write_b16 v17, v3 offset:544
	v_cvt_pk_bf16_f32 v3, v8, v49
	v_lshlrev_b32_e32 v9, 16, v10
	ds_write_b16 v17, v3 offset:816
	v_cvt_pk_bf16_f32 v3, v9, v49
	v_and_b32_e32 v10, 0xffff0000, v10
	v_lshlrev_b32_e32 v14, 16, v11
	v_and_b32_e32 v11, 0xffff0000, v11
	ds_write_b16 v17, v3 offset:1088
	v_cvt_pk_bf16_f32 v3, v10, v49
	ds_write_b16 v17, v3 offset:1360
	v_cvt_pk_bf16_f32 v3, v14, v49
	ds_write_b16 v17, v3 offset:1632
	v_cvt_pk_bf16_f32 v20, v11, v49
	v_ashrrev_i32_e32 v3, 2, v1
	v_and_or_b32 v56, v3, s71, v21
	v_ashrrev_i32_e32 v3, 31, v2
	v_ashrrev_i32_e32 v1, 31, v0
	v_lshlrev_b32_e32 v12, 4, v21
	v_ashrrev_i32_e32 v5, 31, v4
	v_ashrrev_i32_e32 v7, 31, v6
	v_lshlrev_b64 v[2:3], 8, v[2:3]
	v_lshlrev_b64 v[0:1], 8, v[0:1]
	v_lshlrev_b64 v[4:5], 8, v[4:5]
	v_lshlrev_b64 v[6:7], 8, v[6:7]
	v_or_b32_e32 v2, v2, v12
	v_or_b32_e32 v0, v0, v12
	v_or_b32_e32 v4, v4, v12
	v_or_b32_e32 v6, v6, v12
	v_lshl_add_u64 v[12:13], s[58:59], 0, v[2:3]
	ds_write_b16 v17, v20 offset:1904
	v_lshl_add_u64 v[14:15], s[58:59], 0, v[4:5]
	v_lshl_add_u64 v[18:19], s[58:59], 0, v[6:7]
	v_lshl_add_u64 v[0:1], s[58:59], 0, v[0:1]
	v_add_f32_e32 v17, v50, v51
	v_exp_f32_e32 v30, v17
	v_mul_lo_u32 v29, v56, s74
	v_add_u32_e32 v17, v25, v29
	v_lshl_or_b32 v51, v55, 2, v22
	v_or_b32_e32 v26, 1, v51
	v_or_b32_e32 v24, 2, v51
	v_or_b32_e32 v23, 3, v51
	v_sub_u32_e32 v50, v56, v51
	v_sub_u32_e32 v94, v56, v26
	v_sub_u32_e32 v95, v56, v24
	v_sub_u32_e32 v96, v56, v23
	v_cvt_f32_u32_e32 v54, v50
	v_cvt_f32_u32_e32 v88, v94
	v_cvt_f32_u32_e32 v89, v95
	v_cvt_f32_u32_e32 v90, v96
	v_or_b32_e32 v20, 18, v51
	v_sub_u32_e32 v99, v56, v20
	v_lshlrev_b32_e32 v48, 1, v51
	v_cvt_f32_u32_e32 v93, v99
	v_or_b32_e32 v52, 16, v56
	v_sub_u32_e32 v81, v52, v51
	v_cvt_f32_u32_e32 v86, v81
	v_sub_u32_e32 v101, v52, v26
	v_sub_u32_e32 v102, v52, v24
	v_cvt_f32_u32_e32 v107, v101
	v_sub_u32_e32 v103, v52, v23
	v_cvt_f32_u32_e32 v108, v102
	v_cvt_f32_u32_e32 v109, v103
	v_sub_u32_e32 v105, v52, v20
	v_cvt_f32_u32_e32 v111, v105
	s_waitcnt vmcnt(0)
	v_mov_b64_e32 v[8:9], v[148:149]
	v_mov_b64_e32 v[10:11], v[150:151]
	v_lshlrev_b32_e32 v2, 16, v8
	v_cvt_pk_bf16_f32 v2, v2, v49
	v_and_b32_e32 v3, 0xffff0000, v8
	ds_write_b16 v27, v2
	v_cvt_pk_bf16_f32 v2, v3, v49
	v_lshlrev_b32_e32 v4, 16, v9
	ds_write_b16 v27, v2 offset:272
	v_cvt_pk_bf16_f32 v2, v4, v49
	v_and_b32_e32 v5, 0xffff0000, v9
	ds_write_b16 v27, v2 offset:544
	v_cvt_pk_bf16_f32 v2, v5, v49
	v_lshlrev_b32_e32 v6, 16, v10
	ds_write_b16 v27, v2 offset:816
	v_cvt_pk_bf16_f32 v2, v6, v49
	v_and_b32_e32 v7, 0xffff0000, v10
	ds_write_b16 v27, v2 offset:1088
	v_cvt_pk_bf16_f32 v2, v7, v49
	v_lshlrev_b32_e32 v8, 16, v11
	v_and_b32_e32 v9, 0xffff0000, v11
	ds_write_b16 v27, v2 offset:1360
	v_cvt_pk_bf16_f32 v2, v8, v49
	ds_write_b16 v27, v2 offset:1632
	v_cvt_pk_bf16_f32 v28, v9, v49
	global_load_dwordx4 v[0:3], v[0:1], off
	s_nop 0
	global_load_dwordx4 v[4:7], v[12:13], off
	global_load_dwordx4 v[8:11], v[14:15], off
	s_nop 0
	global_load_dwordx4 v[12:15], v[18:19], off
	v_or_b32_e32 v18, v22, v21
	v_mul_u32_u24_e32 v18, 0x88, v18
	v_lshlrev_b32_e32 v18, 1, v18
	v_add_u32_e32 v87, v25, v18
	v_ldexp_f32 v25, v30, s8
	v_sub_f32_e32 v25, 1.0, v25
	v_cmp_gt_f32_e32 vcc, s79, v25
	s_and_b64 s[4:5], vcc, exec
	s_cselect_b32 s4, 32, 0
	v_or_b32_e32 v22, 16, v51
	v_ldexp_f32 v25, v25, s4
	v_sub_u32_e32 v97, v56, v22
	v_log_f32_e32 v35, v25
	v_cvt_f32_u32_e32 v91, v97
	ds_write_b16 v27, v28 offset:1904
	s_waitcnt vmcnt(3)
	ds_write_b128 v32, v[0:3]
	s_waitcnt vmcnt(2)
	ds_write_b128 v33, v[4:7]
	s_waitcnt vmcnt(1)
	ds_write_b128 v34, v[8:11]
	s_waitcnt vmcnt(0)
	ds_write_b128 v31, v[12:15]
	s_waitcnt lgkmcnt(0)
	s_barrier
	ds_read_b128 v[0:3], v87 offset:34816
	v_or_b32_e32 v21, 17, v51
	v_cndmask_b32_e32 v30, 0, v79, vcc
	v_sub_u32_e32 v98, v56, v21
	v_sub_f32_e32 v57, v35, v30
	v_cvt_f32_u32_e32 v92, v98
	v_add3_u32 v25, 0, v29, v48
	v_mul_f32_e32 v29, v57, v54
	v_mul_f32_e32 v30, v57, v88
	v_mul_f32_e32 v36, v57, v89
	v_mul_f32_e32 v44, v57, v90
	v_mul_f32_e32 v62, v57, v91
	v_cmp_gt_f32_e32 vcc, s65, v29
	ds_read_b128 v[4:7], v87 offset:39168
	ds_read_b128 v[8:11], v17
	v_cmp_gt_f32_e64 s[8:9], s65, v30
	ds_read_b128 v[12:15], v87 offset:34880
	ds_read_b128 v[28:31], v17 offset:64
	v_cmp_gt_f32_e64 s[10:11], s65, v36
	ds_read_b128 v[36:39], v17 offset:4352
	ds_read_b128 v[40:43], v87 offset:39232
	v_cmp_gt_f32_e64 s[12:13], s65, v44
	ds_read_b128 v[44:47], v17 offset:4416
	v_cmp_gt_f32_e64 s[14:15], s65, v62
	ds_read_b128 v[62:65], v17 offset:8704
	v_or_b32_e32 v19, 19, v51
	v_sub_u32_e32 v100, v56, v19
	v_cvt_f32_u32_e32 v106, v100
	v_mul_f32_e32 v66, v57, v92
	v_mul_f32_e32 v74, v57, v93
	v_cmp_gt_f32_e64 s[16:17], s65, v66
	ds_read_b128 v[66:69], v17 offset:8768
	v_cmp_gt_f32_e64 s[18:19], s65, v74
	ds_read_b128 v[74:77], v17 offset:13056
	s_waitcnt lgkmcnt(8)
	v_mfma_f32_16x16x32_bf16 v[32:35], v[0:3], v[8:11], 0
	v_mul_f32_e32 v82, v57, v106
	v_cmp_gt_f32_e64 s[20:21], s65, v82
	ds_read_b128 v[82:85], v17 offset:13120
	v_mfma_f32_16x16x32_bf16 v[8:11], v[4:7], v[8:11], 0
	v_mul_f32_e32 v112, v57, v86
	v_cmp_gt_f32_e64 s[22:23], s65, v112
	v_cndmask_b32_e64 v117, 0, v78, s[8:9]
	s_waitcnt lgkmcnt(6)
; __device__ __forceinline__ void tile_mma(f32x4 (&acc)[4][2], const bf16_t* X, int xr0, const bf16_t* Y, int yr0, int fr, int fq) {
; #pragma unroll
;     for (int ks = 0; ks < 4; ++ks) {
;         u32x4 xf[2], yf[4];
; #pragma unroll
;         for (int n = 0; n < 2; ++n) xf[n] = *(const u32x4*)(X + (xr0 + n * 16 + fr) * TS + ks * 32 + fq * 8);
; #pragma unroll
;         for (int m = 0; m < 4; ++m) yf[m] = *(const u32x4*)(Y + (yr0 + m * 16 + fr) * TS + ks * 32 + fq * 8);
; #pragma unroll
;         for (int m = 0; m < 4; ++m)
; #pragma unroll
;             for (int n = 0; n < 2; ++n) acc[m][n] = mfma16(xf[n], yf[m], acc[m][n]);
;     }
; }
; __device__ __forceinline__ void ret_stepC(const Params& p, unsigned char* smem, int u) {
;     ...
;     tile_mma(accP, ks, wc * 32, qs, wr * 64, fr, fq);
;     __syncthreads();
; #pragma unroll
;     for (int m = 0; m < 4; ++m)
; #pragma unroll
;         for (int nn = 0; nn < 2; ++nn) {
;             const int c = wr * 64 + m * 16 + fr, c2 = wc * 32 + nn * 16 + fq * 4;
;             float pv[4];
; #pragma unroll
;             for (int j = 0; j < 4; ++j) { const int df = c - (c2 + j); pv[j] = df >= 0 ? accP[m][nn][j] * exp2f(l2g * (float)df) : 0.f; }
	v_mfma_f32_16x16x32_bf16 v[58:61], v[0:3], v[36:39], 0
	v_cndmask_b32_e64 v118, 0, v78, s[10:11]
	v_cndmask_b32_e64 v112, 0, v78, s[22:23]
	v_cndmask_b32_e64 v119, 0, v78, s[12:13]
	s_waitcnt lgkmcnt(3)
	v_mfma_f32_16x16x32_bf16 v[70:73], v[0:3], v[62:65], 0
	v_cndmask_b32_e64 v120, 0, v78, s[14:15]
	v_cndmask_b32_e64 v121, 0, v78, s[16:17]
	v_cndmask_b32_e64 v122, 0, v78, s[18:19]
	v_mfma_f32_16x16x32_bf16 v[62:65], v[4:7], v[62:65], 0
	v_fmac_f32_e32 v117, v57, v88
	v_fmac_f32_e32 v118, v57, v89
	v_fmac_f32_e32 v112, v57, v86
	v_mfma_f32_16x16x32_bf16 v[36:39], v[4:7], v[36:39], 0
	v_fmac_f32_e32 v119, v57, v90
	v_fmac_f32_e32 v120, v57, v91
	v_fmac_f32_e32 v121, v57, v92
	s_waitcnt lgkmcnt(1)
	v_mfma_f32_16x16x32_bf16 v[0:3], v[0:3], v[74:77], 0
	v_fmac_f32_e32 v122, v57, v93
	v_cndmask_b32_e32 v27, 0, v78, vcc
	v_cndmask_b32_e64 v123, 0, v78, s[20:21]
	v_mfma_f32_16x16x32_bf16 v[32:35], v[12:15], v[28:31], v[32:35]
	v_fmac_f32_e32 v27, v57, v54
	v_fmac_f32_e32 v123, v57, v106
	v_exp_f32_e32 v27, v27
	v_mfma_f32_16x16x32_bf16 v[8:11], v[40:43], v[28:31], v[8:11]
	v_exp_f32_e32 v117, v117
	v_sub_u32_e32 v104, v52, v21
	v_cvt_f32_u32_e32 v110, v104
	v_mfma_f32_16x16x32_bf16 v[28:31], v[12:15], v[44:47], v[58:61]
	v_cndmask_b32_e32 v54, 0, v80, vcc
	v_cndmask_b32_e64 v124, 0, v80, s[8:9]
	v_mul_f32_e32 v113, v57, v107
	v_mfma_f32_16x16x32_bf16 v[58:61], v[40:43], v[66:69], v[62:65]
	v_cndmask_b32_e64 v125, 0, v80, s[10:11]
	v_cndmask_b32_e64 v128, 0, v80, s[16:17]
	v_cndmask_b32_e64 v129, 0, v80, s[18:19]
	ds_read_b128 v[62:65], v87 offset:34944
	v_mfma_f32_16x16x32_bf16 v[4:7], v[4:7], v[74:77], 0
	v_cndmask_b32_e64 v106, 0, v80, s[20:21]
	v_cndmask_b32_e64 v130, 0, v80, s[22:23]
	v_ldexp_f32 v27, v27, v54
	v_mfma_f32_16x16x32_bf16 v[36:39], v[40:43], v[44:47], v[36:39]
	v_ldexp_f32 v54, v117, v124
	v_mul_f32_e32 v114, v57, v108
	v_cmp_gt_f32_e64 s[24:25], s65, v113
	v_mfma_f32_16x16x32_bf16 v[44:47], v[12:15], v[66:69], v[70:73]
	v_cndmask_b32_e64 v126, 0, v80, s[12:13]
	v_cmp_lt_i32_e64 s[8:9], -1, v94
	v_mul_f32_e32 v115, v57, v109
	s_waitcnt lgkmcnt(1)
	v_mfma_f32_16x16x32_bf16 v[0:3], v[12:15], v[82:85], v[0:3]
	ds_read_b128 v[12:15], v87 offset:39296
	ds_read_b128 v[66:69], v17 offset:128
	v_cndmask_b32_e64 v113, 0, v78, s[24:25]
	v_cmp_gt_f32_e64 s[26:27], s65, v114
	v_mfma_f32_16x16x32_bf16 v[4:7], v[40:43], v[82:85], v[4:7]
	ds_read_b128 v[40:43], v87 offset:35008
	ds_read_b128 v[70:73], v17 offset:192
	ds_read_b128 v[74:77], v17 offset:4480
	ds_read_b128 v[82:85], v87 offset:39360
	ds_read_b128 v[86:89], v17 offset:8832
	s_waitcnt lgkmcnt(5)
	v_mfma_f32_16x16x32_bf16 v[32:35], v[62:65], v[66:69], v[32:35]
	ds_read_b128 v[90:93], v17 offset:13184
	v_cndmask_b32_e64 v127, 0, v80, s[14:15]
	v_mul_f32_e32 v116, v57, v110
	v_mfma_f32_16x16x32_bf16 v[8:11], v[12:15], v[66:69], v[8:11]
	ds_read_b128 v[66:69], v17 offset:4544
	v_cndmask_b32_e64 v114, 0, v78, s[26:27]
	v_cmp_gt_f32_e64 s[28:29], s65, v115
	s_waitcnt lgkmcnt(4)
	v_mfma_f32_16x16x32_bf16 v[28:31], v[62:65], v[74:77], v[28:31]
	v_fmac_f32_e32 v113, v57, v107
	v_cndmask_b32_e64 v115, 0, v78, s[28:29]
	v_cmp_gt_f32_e64 s[30:31], s65, v116
	v_mfma_f32_16x16x32_bf16 v[36:39], v[12:15], v[74:77], v[36:39]
	ds_read_b128 v[74:77], v17 offset:8896
	v_fmac_f32_e32 v114, v57, v108
	v_cndmask_b32_e64 v116, 0, v78, s[30:31]
	s_waitcnt lgkmcnt(3)
	v_mfma_f32_16x16x32_bf16 v[44:47], v[62:65], v[86:89], v[44:47]
	v_fmac_f32_e32 v115, v57, v109
	v_fmac_f32_e32 v116, v57, v110
	v_cndmask_b32_e64 v107, 0, v80, s[24:25]
	v_mfma_f32_16x16x32_bf16 v[58:61], v[12:15], v[86:89], v[58:61]
	ds_read_b128 v[86:89], v17 offset:13248
	v_cndmask_b32_e64 v108, 0, v80, s[26:27]
	v_cmp_lt_i32_e32 vcc, -1, v50
	s_waitcnt lgkmcnt(3)
	v_mfma_f32_16x16x32_bf16 v[0:3], v[62:65], v[90:93], v[0:3]
	v_exp_f32_e32 v62, v118
	v_exp_f32_e32 v63, v119
	v_exp_f32_e32 v64, v120
	v_mfma_f32_16x16x32_bf16 v[12:15], v[12:15], v[90:93], v[4:7]
	v_ldexp_f32 v62, v62, v125
	v_ldexp_f32 v63, v63, v126
	v_ldexp_f32 v64, v64, v127
	v_exp_f32_e32 v4, v121
	v_exp_f32_e32 v5, v122
	v_exp_f32_e32 v6, v123
	v_mfma_f32_16x16x32_bf16 v[32:35], v[40:43], v[70:73], v[32:35]
	v_exp_f32_e32 v7, v112
	v_exp_f32_e32 v65, v113
	v_exp_f32_e32 v90, v114
	v_mfma_f32_16x16x32_bf16 v[8:11], v[82:85], v[70:73], v[8:11]
	v_exp_f32_e32 v70, v115
	v_exp_f32_e32 v71, v116
	v_ldexp_f32 v65, v65, v107
	s_waitcnt lgkmcnt(2)
	v_mfma_f32_16x16x32_bf16 v[28:31], v[40:43], v[66:69], v[28:31]
	v_cndmask_b32_e64 v109, 0, v80, s[28:29]
	s_nop 1
	v_mul_f32_e32 v8, v64, v8
	v_ldexp_f32 v72, v90, v108
	v_mfma_f32_16x16x32_bf16 v[36:39], v[82:85], v[66:69], v[36:39]
	v_ldexp_f32 v66, v4, v128
	v_ldexp_f32 v67, v5, v129
	v_ldexp_f32 v68, v6, v106
	v_ldexp_f32 v69, v7, v130
	s_waitcnt lgkmcnt(0)
	v_mfma_f32_16x16x32_bf16 v[4:7], v[40:43], v[86:89], v[0:3]
	v_mul_f32_e32 v9, v66, v9
	v_mul_f32_e32 v10, v67, v10
	v_mul_f32_e32 v11, v68, v11
	v_mfma_f32_16x16x32_bf16 v[0:3], v[82:85], v[86:89], v[12:15]
	v_mul_f32_e32 v28, v69, v28
	s_barrier
; __device__ __forceinline__ unsigned cvt_pk_bf16(float lo, float hi) { unsigned r; asm volatile("v_cvt_pk_bf16_f32 %0, %1, %2" : "=v"(r) : "v"(lo), "v"(hi)); return r; }
; __device__ __forceinline__ void ret_stepC(const Params& p, unsigned char* smem, int u) {
;     ...
; #pragma unroll
;     for (int m = 0; m < 4; ++m)
; #pragma unroll
;         for (int nn = 0; nn < 2; ++nn) {
;             const int c = wr * 64 + m * 16 + fr, c2 = wc * 32 + nn * 16 + fq * 4;
;             float pv[4];
; #pragma unroll
;             for (int j = 0; j < 4; ++j) { const int df = c - (c2 + j); pv[j] = df >= 0 ? accP[m][nn][j] * exp2f(l2g * (float)df) : 0.f; }
;             u32x2 w; w.x = cvt_pk_bf16(pv[0], pv[1]); w.y = cvt_pk_bf16(pv[2], pv[3]);
;             *(u32x2*)(ks + c * TS + c2) = w;
;         }
	s_nop 0
	v_mul_f32_e32 v13, v54, v33
	v_mul_f32_e32 v14, v62, v34
	v_cndmask_b32_e64 v13, 0, v13, s[8:9]
	v_cmp_lt_i32_e64 s[8:9], -1, v95
	v_mul_f32_e32 v15, v63, v35
	v_mul_f32_e32 v12, v27, v32
	v_cndmask_b32_e64 v14, 0, v14, s[8:9]
	v_cmp_lt_i32_e64 s[8:9], -1, v96
	v_mul_f32_e32 v29, v65, v29
	s_nop 0
	v_cndmask_b32_e64 v15, 0, v15, s[8:9]
	v_cmp_lt_i32_e64 s[8:9], -1, v97
	v_cndmask_b32_e32 v12, 0, v12, vcc
	v_cndmask_b32_e64 v110, 0, v80, s[30:31]
	v_cndmask_b32_e64 v33, 0, v8, s[8:9]
	v_cmp_lt_i32_e64 s[8:9], -1, v98
	v_cvt_pk_bf16_f32 v8, v12, v13
	v_ldexp_f32 v70, v70, v109
	v_mul_f32_e32 v30, v72, v30
	v_cndmask_b32_e64 v34, 0, v9, s[8:9]
	v_cmp_lt_i32_e64 s[8:9], -1, v99
	v_cvt_pk_bf16_f32 v9, v14, v15
	ds_write_b64 v25, v[8:9] offset:34816
	v_cvt_pk_bf16_f32 v8, v33, v34
	v_ldexp_f32 v71, v71, v110
	v_cndmask_b32_e64 v10, 0, v10, s[8:9]
	v_cmp_lt_i32_e64 s[8:9], -1, v100
	v_mul_f32_e32 v31, v70, v31
	v_mul_f32_e32 v27, v27, v36
	v_cndmask_b32_e64 v11, 0, v11, s[8:9]
	v_cmp_lt_i32_e64 s[8:9], -1, v81
	v_cvt_pk_bf16_f32 v9, v10, v11
	ds_write_b64 v25, v[8:9] offset:34848
	v_mul_f32_e32 v32, v71, v37
	v_cndmask_b32_e64 v28, 0, v28, s[8:9]
	v_cmp_lt_i32_e64 s[8:9], -1, v101
	v_cndmask_b32_e32 v27, 0, v27, vcc
	v_cmp_lt_i32_e32 vcc, -1, v104
	v_cndmask_b32_e64 v29, 0, v29, s[8:9]
	v_cmp_lt_i32_e64 s[8:9], -1, v102
	v_cvt_pk_bf16_f32 v8, v28, v29
	v_cndmask_b32_e32 v32, 0, v32, vcc
	v_or_b32_e32 v54, 32, v56
	v_cndmask_b32_e64 v30, 0, v30, s[8:9]
	v_cmp_lt_i32_e64 s[8:9], -1, v103
	v_mfma_f32_16x16x32_bf16 v[44:47], v[40:43], v[74:77], v[44:47]
	v_or_b32_e32 v50, 48, v56
	v_cndmask_b32_e64 v31, 0, v31, s[8:9]
	v_cvt_pk_bf16_f32 v9, v30, v31
	ds_write_b64 v25, v[8:9] offset:39168
	v_mul_f32_e32 v8, v57, v111
	v_cmp_gt_f32_e32 vcc, s65, v8
	v_sub_u32_e32 v9, v52, v19
	v_cvt_f32_u32_e32 v10, v9
	v_cndmask_b32_e32 v8, 0, v78, vcc
	v_fmac_f32_e32 v8, v57, v111
	v_exp_f32_e32 v8, v8
	v_cndmask_b32_e32 v11, 0, v80, vcc
	v_cmp_lt_i32_e64 s[8:9], -1, v105
	v_mfma_f32_16x16x32_bf16 v[58:61], v[82:85], v[74:77], v[58:61]
	v_ldexp_f32 v8, v8, v11
	v_mul_f32_e32 v11, v57, v10
	v_cmp_gt_f32_e32 vcc, s65, v11
	v_mul_f32_e32 v8, v8, v38
	s_nop 0
	v_cndmask_b32_e32 v11, 0, v78, vcc
	v_fmac_f32_e32 v11, v57, v10
	v_exp_f32_e32 v10, v11
	v_cndmask_b32_e64 v11, 0, v8, s[8:9]
	v_cndmask_b32_e32 v8, 0, v80, vcc
	v_cmp_lt_i32_e32 vcc, -1, v9
	v_ldexp_f32 v8, v10, v8
	v_sub_u32_e32 v10, v54, v51
	v_cvt_f32_u32_e32 v12, v10
	v_mul_f32_e32 v8, v8, v39
	v_cndmask_b32_e32 v9, 0, v8, vcc
	v_cvt_pk_bf16_f32 v8, v27, v32
	v_cvt_pk_bf16_f32 v9, v11, v9
	ds_write_b64 v25, v[8:9] offset:39200
	v_mul_f32_e32 v8, v57, v12
	v_cmp_gt_f32_e32 vcc, s65, v8
	v_sub_u32_e32 v9, v54, v26
	v_cvt_f32_u32_e32 v11, v9
	v_cndmask_b32_e32 v8, 0, v78, vcc
	v_fmac_f32_e32 v8, v57, v12
	v_exp_f32_e32 v8, v8
	v_cndmask_b32_e32 v12, 0, v80, vcc
	v_cmp_lt_i32_e64 s[8:9], -1, v10
	v_ldexp_f32 v8, v8, v12
	v_mul_f32_e32 v12, v57, v11
	v_cmp_gt_f32_e32 vcc, s65, v12
	v_mul_f32_e32 v8, v8, v44
	v_cndmask_b32_e64 v8, 0, v8, s[8:9]
	v_cndmask_b32_e32 v12, 0, v78, vcc
	v_fmac_f32_e32 v12, v57, v11
	v_exp_f32_e32 v11, v12
	v_cndmask_b32_e32 v10, 0, v80, vcc
	v_cmp_lt_i32_e32 vcc, -1, v9
	v_ldexp_f32 v10, v11, v10
	v_sub_u32_e32 v11, v54, v24
	v_cvt_f32_u32_e32 v12, v11
	v_mul_f32_e32 v10, v10, v45
	v_cndmask_b32_e32 v9, 0, v10, vcc
	v_cmp_lt_i32_e64 s[8:9], -1, v11
	v_mul_f32_e32 v10, v57, v12
	v_cmp_gt_f32_e32 vcc, s65, v10
	v_cvt_pk_bf16_f32 v8, v8, v9
	s_nop 1
	v_cndmask_b32_e32 v10, 0, v78, vcc
	v_fmac_f32_e32 v10, v57, v12
	v_sub_u32_e32 v12, v54, v23
	v_exp_f32_e32 v10, v10
	v_cvt_f32_u32_e32 v13, v12
	v_cndmask_b32_e32 v14, 0, v80, vcc
	v_ldexp_f32 v10, v10, v14
	v_mul_f32_e32 v14, v57, v13
	v_cmp_gt_f32_e32 vcc, s65, v14
	v_mul_f32_e32 v10, v10, v46
	v_cndmask_b32_e64 v10, 0, v10, s[8:9]
	v_cndmask_b32_e32 v14, 0, v78, vcc
	v_fmac_f32_e32 v14, v57, v13
	v_exp_f32_e32 v13, v14
	v_cndmask_b32_e32 v11, 0, v80, vcc
	v_cmp_lt_i32_e32 vcc, -1, v12
	v_sub_u32_e32 v12, v54, v22
	v_ldexp_f32 v11, v13, v11
	v_cvt_f32_u32_e32 v13, v12
	v_mul_f32_e32 v11, v11, v47
	v_cndmask_b32_e32 v11, 0, v11, vcc
	v_cvt_pk_bf16_f32 v9, v10, v11
	ds_write_b64 v25, v[8:9] offset:43520
	v_mul_f32_e32 v8, v57, v13
	v_cmp_gt_f32_e32 vcc, s65, v8
	v_sub_u32_e32 v9, v54, v21
	v_cvt_f32_u32_e32 v10, v9
	v_cndmask_b32_e32 v8, 0, v78, vcc
	v_fmac_f32_e32 v8, v57, v13
	v_exp_f32_e32 v8, v8
	v_cndmask_b32_e32 v11, 0, v80, vcc
	v_cmp_lt_i32_e64 s[8:9], -1, v12
	v_ldexp_f32 v8, v8, v11
	v_mul_f32_e32 v11, v57, v10
	v_cmp_gt_f32_e32 vcc, s65, v11
	v_mul_f32_e32 v8, v8, v58
	v_cndmask_b32_e64 v8, 0, v8, s[8:9]
	v_cndmask_b32_e32 v11, 0, v78, vcc
	v_fmac_f32_e32 v11, v57, v10
	v_exp_f32_e32 v10, v11
	v_cndmask_b32_e32 v11, 0, v80, vcc
	v_cmp_lt_i32_e32 vcc, -1, v9
	v_ldexp_f32 v10, v10, v11
	v_sub_u32_e32 v11, v54, v20
	v_cvt_f32_u32_e32 v12, v11
	v_mul_f32_e32 v10, v10, v59
	v_cndmask_b32_e32 v9, 0, v10, vcc
	v_cmp_lt_i32_e64 s[8:9], -1, v11
	v_mul_f32_e32 v10, v57, v12
	v_cmp_gt_f32_e32 vcc, s65, v10
	v_cvt_pk_bf16_f32 v8, v8, v9
	s_nop 1
	v_cndmask_b32_e32 v10, 0, v78, vcc
	v_fmac_f32_e32 v10, v57, v12
	v_sub_u32_e32 v12, v54, v19
	v_exp_f32_e32 v10, v10
	v_cvt_f32_u32_e32 v13, v12
	v_cndmask_b32_e32 v14, 0, v80, vcc
	v_ldexp_f32 v10, v10, v14
	v_mul_f32_e32 v14, v57, v13
	v_cmp_gt_f32_e32 vcc, s65, v14
	v_mul_f32_e32 v10, v10, v60
	v_cndmask_b32_e64 v10, 0, v10, s[8:9]
	v_cndmask_b32_e32 v14, 0, v78, vcc
	v_fmac_f32_e32 v14, v57, v13
	v_exp_f32_e32 v13, v14
	v_cndmask_b32_e32 v11, 0, v80, vcc
	v_cmp_lt_i32_e32 vcc, -1, v12
	v_sub_u32_e32 v12, v50, v51
	v_ldexp_f32 v11, v13, v11
	v_cvt_f32_u32_e32 v13, v12
; __device__ __forceinline__ unsigned cvt_pk_bf16(float lo, float hi) { unsigned r; asm volatile("v_cvt_pk_bf16_f32 %0, %1, %2" : "=v"(r) : "v"(lo), "v"(hi)); return r; }
; __device__ __forceinline__ void ret_stepC(const Params& p, unsigned char* smem, int u) {
;     ...
; #pragma unroll
;     for (int m = 0; m < 4; ++m)
; #pragma unroll
;         for (int nn = 0; nn < 2; ++nn) {
;             const int c = wr * 64 + m * 16 + fr, c2 = wc * 32 + nn * 16 + fq * 4;
;             float pv[4];
; #pragma unroll
;             for (int j = 0; j < 4; ++j) { const int df = c - (c2 + j); pv[j] = df >= 0 ? accP[m][nn][j] * exp2f(l2g * (float)df) : 0.f; }
;             u32x2 w; w.x = cvt_pk_bf16(pv[0], pv[1]); w.y = cvt_pk_bf16(pv[2], pv[3]);
;             *(u32x2*)(ks + c * TS + c2) = w;
;         }
;     __syncthreads();
;     f32x4 a1[4][2], a2[4][2];
; #pragma unroll
;     for (int m = 0; m < 4; ++m) { a1[m][0] = (f32x4){0, 0, 0, 0}; a1[m][1] = a1[m][0]; a2[m][0] = a1[m][0]; a2[m][1] = a1[m][0]; }
;     tile_mma(a1, vT, wc * 32, ks, wr * 64, fr, fq);
	v_mul_f32_e32 v11, v11, v61
	v_cndmask_b32_e32 v11, 0, v11, vcc
	v_cvt_pk_bf16_f32 v9, v10, v11
	ds_write_b64 v25, v[8:9] offset:43552
	v_mul_f32_e32 v8, v57, v13
	v_cmp_gt_f32_e32 vcc, s65, v8
	v_sub_u32_e32 v9, v50, v26
	v_cvt_f32_u32_e32 v10, v9
	v_cndmask_b32_e32 v8, 0, v78, vcc
	v_fmac_f32_e32 v8, v57, v13
	v_exp_f32_e32 v8, v8
	v_cndmask_b32_e32 v11, 0, v80, vcc
	v_cmp_lt_i32_e64 s[8:9], -1, v12
	v_ldexp_f32 v8, v8, v11
	v_mul_f32_e32 v4, v8, v4
	v_mul_f32_e32 v8, v57, v10
	v_cmp_gt_f32_e32 vcc, s65, v8
	v_cndmask_b32_e64 v4, 0, v4, s[8:9]
	s_nop 0
	v_cndmask_b32_e32 v8, 0, v78, vcc
	v_fmac_f32_e32 v8, v57, v10
	v_exp_f32_e32 v8, v8
	v_cndmask_b32_e32 v10, 0, v80, vcc
	v_cmp_lt_i32_e32 vcc, -1, v9
	v_sub_u32_e32 v9, v50, v23
	v_ldexp_f32 v8, v8, v10
	v_sub_u32_e32 v10, v50, v24
	v_cvt_f32_u32_e32 v11, v10
	v_mul_f32_e32 v5, v8, v5
	v_cndmask_b32_e32 v5, 0, v5, vcc
	v_cmp_lt_i32_e64 s[8:9], -1, v10
	v_mul_f32_e32 v8, v57, v11
	v_cmp_gt_f32_e32 vcc, s65, v8
	v_cvt_pk_bf16_f32 v4, v4, v5
	s_nop 1
	v_cndmask_b32_e32 v8, 0, v78, vcc
	v_fmac_f32_e32 v8, v57, v11
	v_exp_f32_e32 v8, v8
	v_cvt_f32_u32_e32 v11, v9
	v_cndmask_b32_e32 v12, 0, v80, vcc
	v_ldexp_f32 v8, v8, v12
	v_mul_f32_e32 v6, v8, v6
	v_mul_f32_e32 v8, v57, v11
	v_cmp_gt_f32_e32 vcc, s65, v8
	v_cndmask_b32_e64 v6, 0, v6, s[8:9]
	s_nop 0
	v_cndmask_b32_e32 v8, 0, v78, vcc
	v_fmac_f32_e32 v8, v57, v11
	v_exp_f32_e32 v8, v8
	v_cndmask_b32_e32 v10, 0, v80, vcc
	v_cmp_lt_i32_e32 vcc, -1, v9
	v_ldexp_f32 v8, v8, v10
	v_mul_f32_e32 v7, v8, v7
	v_sub_u32_e32 v8, v50, v22
	v_cvt_f32_u32_e32 v9, v8
	v_cndmask_b32_e32 v7, 0, v7, vcc
	v_cvt_pk_bf16_f32 v5, v6, v7
	ds_write_b64 v25, v[4:5] offset:47872
	v_mul_f32_e32 v4, v57, v9
	v_cmp_gt_f32_e32 vcc, s65, v4
	v_sub_u32_e32 v5, v50, v21
	v_cvt_f32_u32_e32 v6, v5
	v_cndmask_b32_e32 v4, 0, v78, vcc
	v_fmac_f32_e32 v4, v57, v9
	v_exp_f32_e32 v4, v4
	v_cndmask_b32_e32 v7, 0, v80, vcc
	v_cmp_lt_i32_e64 s[8:9], -1, v8
	v_ldexp_f32 v4, v4, v7
	v_mul_f32_e32 v0, v4, v0
	v_mul_f32_e32 v4, v57, v6
	v_cmp_gt_f32_e32 vcc, s65, v4
	v_cndmask_b32_e64 v0, 0, v0, s[8:9]
	s_nop 0
	v_cndmask_b32_e32 v4, 0, v78, vcc
	v_fmac_f32_e32 v4, v57, v6
	v_exp_f32_e32 v4, v4
	v_cndmask_b32_e32 v6, 0, v80, vcc
	v_cmp_lt_i32_e32 vcc, -1, v5
	v_sub_u32_e32 v5, v50, v19
	v_ldexp_f32 v4, v4, v6
	v_sub_u32_e32 v6, v50, v20
	v_cvt_f32_u32_e32 v7, v6
	v_mul_f32_e32 v1, v4, v1
	v_cndmask_b32_e32 v1, 0, v1, vcc
	v_cmp_lt_i32_e64 s[8:9], -1, v6
	v_mul_f32_e32 v4, v57, v7
	v_cmp_gt_f32_e32 vcc, s65, v4
	v_cvt_pk_bf16_f32 v0, v0, v1
	v_add3_u32 v19, s77, v16, v18
	v_add3_u32 v16, s78, v16, v18
	v_cndmask_b32_e32 v4, 0, v78, vcc
	v_fmac_f32_e32 v4, v57, v7
	v_exp_f32_e32 v4, v4
	v_cvt_f32_u32_e32 v7, v5
	v_cndmask_b32_e32 v8, 0, v80, vcc
	v_ldexp_f32 v4, v4, v8
	v_mul_f32_e32 v2, v4, v2
	v_mul_f32_e32 v4, v57, v7
	v_cmp_gt_f32_e32 vcc, s65, v4
	v_cndmask_b32_e64 v2, 0, v2, s[8:9]
	v_cmp_lt_i32_e64 s[8:9], v170, v168
	v_cndmask_b32_e32 v4, 0, v78, vcc
	v_fmac_f32_e32 v4, v57, v7
	v_exp_f32_e32 v4, v4
	v_cndmask_b32_e32 v6, 0, v80, vcc
	v_cmp_lt_i32_e32 vcc, -1, v5
	v_ldexp_f32 v4, v4, v6
	v_mul_f32_e32 v3, v4, v3
	v_cndmask_b32_e32 v3, 0, v3, vcc
	v_cvt_pk_bf16_f32 v1, v2, v3
	ds_write_b64 v25, v[0:1] offset:47904
	s_waitcnt lgkmcnt(0)
	s_barrier
	ds_read_b128 v[0:3], v19
	ds_read_b128 v[4:7], v17 offset:34816
	ds_read_b128 v[8:11], v19 offset:64
	ds_read_b128 v[12:15], v17 offset:34880
	ds_read_b128 v[24:27], v19 offset:4352
	ds_read_b128 v[28:31], v19 offset:4416
	ds_read_b128 v[32:35], v17 offset:39168
	ds_read_b128 v[36:39], v17 offset:39232
	ds_read_b128 v[44:47], v17 offset:43520
	ds_read_b128 v[58:61], v17 offset:43584
	ds_read_b128 v[66:69], v17 offset:47872
	ds_read_b128 v[70:73], v17 offset:47936
	s_waitcnt lgkmcnt(10)
	v_mfma_f32_16x16x32_bf16 v[20:23], v[0:3], v[4:7], 0
	s_waitcnt lgkmcnt(7)
	v_mfma_f32_16x16x32_bf16 v[4:7], v[24:27], v[4:7], 0
	s_waitcnt lgkmcnt(5)
	v_mfma_f32_16x16x32_bf16 v[40:43], v[0:3], v[32:35], 0
	v_mfma_f32_16x16x32_bf16 v[32:35], v[24:27], v[32:35], 0
	s_waitcnt lgkmcnt(3)
	v_mfma_f32_16x16x32_bf16 v[62:65], v[0:3], v[44:47], 0
	s_waitcnt lgkmcnt(1)
	v_mfma_f32_16x16x32_bf16 v[0:3], v[0:3], v[66:69], 0
	v_mfma_f32_16x16x32_bf16 v[20:23], v[8:11], v[12:15], v[20:23]
	v_mfma_f32_16x16x32_bf16 v[4:7], v[28:31], v[12:15], v[4:7]
	v_mfma_f32_16x16x32_bf16 v[12:15], v[8:11], v[36:39], v[40:43]
	v_mfma_f32_16x16x32_bf16 v[32:35], v[28:31], v[36:39], v[32:35]
	v_mfma_f32_16x16x32_bf16 v[36:39], v[8:11], v[58:61], v[62:65]
	s_waitcnt lgkmcnt(0)
	v_mfma_f32_16x16x32_bf16 v[0:3], v[8:11], v[70:73], v[0:3]
	ds_read_b128 v[8:11], v19 offset:128
	v_mfma_f32_16x16x32_bf16 v[44:47], v[24:27], v[44:47], 0
	v_mfma_f32_16x16x32_bf16 v[24:27], v[24:27], v[66:69], 0
	v_mfma_f32_16x16x32_bf16 v[40:43], v[28:31], v[58:61], v[44:47]
	v_mfma_f32_16x16x32_bf16 v[24:27], v[28:31], v[70:73], v[24:27]
	ds_read_b128 v[28:31], v17 offset:34944
	s_nop 3
	ds_read_b128 v[44:47], v19 offset:192
	ds_read_b128 v[58:61], v17 offset:35008
	ds_read_b128 v[62:65], v19 offset:4480
	ds_read_b128 v[66:69], v19 offset:4544
	s_waitcnt lgkmcnt(4)
	v_mfma_f32_16x16x32_bf16 v[20:23], v[8:11], v[28:31], v[20:23]
	s_waitcnt lgkmcnt(1)
	v_mfma_f32_16x16x32_bf16 v[4:7], v[62:65], v[28:31], v[4:7]
	ds_read_b128 v[28:31], v17 offset:39296
	ds_read_b128 v[70:73], v17 offset:39360
	s_waitcnt lgkmcnt(1)
	v_mfma_f32_16x16x32_bf16 v[12:15], v[8:11], v[28:31], v[12:15]
	v_mfma_f32_16x16x32_bf16 v[28:31], v[62:65], v[28:31], v[32:35]
	s_nop 2
	ds_read_b128 v[32:35], v17 offset:43648
	ds_read_b128 v[74:77], v17 offset:43712
	s_waitcnt lgkmcnt(1)
; __device__ __forceinline__ void ret_stepC(const Params& p, unsigned char* smem, int u) {
;     ...
;     tile_mma(a1, vT, wc * 32, ks, wr * 64, fr, fq);
;     tile_mma(a2, rs, wc * 32, qs, wr * 64, fr, fq);
;     __syncthreads();
;     float* red = (float*)smem;
;     float mean[4], rstd[4];
; #pragma unroll
;     for (int m = 0; m < 4; ++m) {
;         const int c = wr * 64 + m * 16 + fr; const float xi = exp2f(l2g * (float)(c + 1));
;         float s = 0.f, s2 = 0.f;
; #pragma unroll
;         for (int nn = 0; nn < 2; ++nn)
; #pragma unroll
;             for (int j = 0; j < 4; ++j) { const float o = a1[m][nn][j] + xi * a2[m][nn][j]; a1[m][nn][j] = o; s += o; s2 += o * o; }
;         s += __shfl_xor(s, 16); s += __shfl_xor(s, 32); s2 += __shfl_xor(s2, 16); s2 += __shfl_xor(s2, 32);
;         if (fq == 0) { red[(c * 4 + wc) * 2] = s; red[(c * 4 + wc) * 2 + 1] = s2; }
;     }
	v_mfma_f32_16x16x32_bf16 v[82:85], v[8:11], v[32:35], v[36:39]
	v_mfma_f32_16x16x32_bf16 v[32:35], v[62:65], v[32:35], v[40:43]
	s_nop 1
	ds_read_b128 v[36:39], v17 offset:48000
	ds_read_b128 v[40:43], v17 offset:48064
	s_waitcnt lgkmcnt(1)
	v_mfma_f32_16x16x32_bf16 v[0:3], v[8:11], v[36:39], v[0:3]
	v_mfma_f32_16x16x32_bf16 v[24:27], v[62:65], v[36:39], v[24:27]
	v_mfma_f32_16x16x32_bf16 v[36:39], v[44:47], v[70:73], v[12:15]
	s_nop 2
	ds_read_b128 v[12:15], v16
	v_mfma_f32_16x16x32_bf16 v[62:65], v[44:47], v[58:61], v[20:23]
	v_mfma_f32_16x16x32_bf16 v[58:61], v[66:69], v[58:61], v[4:7]
	v_mfma_f32_16x16x32_bf16 v[28:31], v[66:69], v[70:73], v[28:31]
	v_mfma_f32_16x16x32_bf16 v[20:23], v[44:47], v[74:77], v[82:85]
	v_mfma_f32_16x16x32_bf16 v[8:11], v[66:69], v[74:77], v[32:35]
	s_waitcnt lgkmcnt(1)
	v_mfma_f32_16x16x32_bf16 v[4:7], v[44:47], v[40:43], v[0:3]
	v_mfma_f32_16x16x32_bf16 v[0:3], v[66:69], v[40:43], v[24:27]
	s_nop 2
	ds_read_b128 v[24:27], v17
	ds_read_b128 v[32:35], v16 offset:64
	ds_read_b128 v[40:43], v17 offset:64
	ds_read_b128 v[66:69], v16 offset:4352
	ds_read_b128 v[70:73], v16 offset:4416
	ds_read_b128 v[74:77], v17 offset:4352
	ds_read_b128 v[82:85], v17 offset:4416
	ds_read_b128 v[90:93], v17 offset:8704
	ds_read_b128 v[94:97], v17 offset:8768
	ds_read_b128 v[102:105], v17 offset:13056
	ds_read_b128 v[106:109], v17 offset:13120
	s_waitcnt lgkmcnt(10)
	v_mfma_f32_16x16x32_bf16 v[44:47], v[12:15], v[24:27], 0
	s_waitcnt lgkmcnt(7)
	v_mfma_f32_16x16x32_bf16 v[24:27], v[66:69], v[24:27], 0
	s_waitcnt lgkmcnt(5)
	v_mfma_f32_16x16x32_bf16 v[86:89], v[12:15], v[74:77], 0
	v_mfma_f32_16x16x32_bf16 v[74:77], v[66:69], v[74:77], 0
	s_waitcnt lgkmcnt(3)
	v_mfma_f32_16x16x32_bf16 v[98:101], v[12:15], v[90:93], 0
	s_waitcnt lgkmcnt(1)
	v_mfma_f32_16x16x32_bf16 v[12:15], v[12:15], v[102:105], 0
	v_mfma_f32_16x16x32_bf16 v[44:47], v[32:35], v[40:43], v[44:47]
	v_mfma_f32_16x16x32_bf16 v[24:27], v[70:73], v[40:43], v[24:27]
	v_mfma_f32_16x16x32_bf16 v[40:43], v[32:35], v[82:85], v[86:89]
	v_mfma_f32_16x16x32_bf16 v[74:77], v[70:73], v[82:85], v[74:77]
	v_mfma_f32_16x16x32_bf16 v[82:85], v[32:35], v[94:97], v[98:101]
	s_waitcnt lgkmcnt(0)
	v_mfma_f32_16x16x32_bf16 v[12:15], v[32:35], v[106:109], v[12:15]
	ds_read_b128 v[32:35], v16 offset:128
	v_mfma_f32_16x16x32_bf16 v[90:93], v[66:69], v[90:93], 0
	v_mfma_f32_16x16x32_bf16 v[66:69], v[66:69], v[102:105], 0
	v_mfma_f32_16x16x32_bf16 v[86:89], v[70:73], v[94:97], v[90:93]
	v_mfma_f32_16x16x32_bf16 v[66:69], v[70:73], v[106:109], v[66:69]
	ds_read_b128 v[70:73], v17 offset:128
	s_nop 3
	ds_read_b128 v[90:93], v16 offset:192
	ds_read_b128 v[94:97], v17 offset:192
	ds_read_b128 v[98:101], v16 offset:4480
	ds_read_b128 v[102:105], v16 offset:4544
	s_waitcnt lgkmcnt(4)
	v_mfma_f32_16x16x32_bf16 v[44:47], v[32:35], v[70:73], v[44:47]
	s_waitcnt lgkmcnt(1)
	v_mfma_f32_16x16x32_bf16 v[24:27], v[98:101], v[70:73], v[24:27]
	ds_read_b128 v[70:73], v17 offset:4480
	ds_read_b128 v[106:109], v17 offset:4544
	s_waitcnt lgkmcnt(1)
	v_mfma_f32_16x16x32_bf16 v[40:43], v[32:35], v[70:73], v[40:43]
	v_mfma_f32_16x16x32_bf16 v[70:73], v[98:101], v[70:73], v[74:77]
	s_nop 2
	ds_read_b128 v[74:77], v17 offset:8832
	ds_read_b128 v[110:113], v17 offset:8896
	s_waitcnt lgkmcnt(1)
	v_mfma_f32_16x16x32_bf16 v[82:85], v[32:35], v[74:77], v[82:85]
	v_mfma_f32_16x16x32_bf16 v[74:77], v[98:101], v[74:77], v[86:89]
	s_nop 2
	ds_read_b128 v[86:89], v17 offset:13184
	ds_read_b128 v[114:117], v17 offset:13248
	s_waitcnt lgkmcnt(0)
	s_barrier
	v_mfma_f32_16x16x32_bf16 v[12:15], v[32:35], v[86:89], v[12:15]
	v_mfma_f32_16x16x32_bf16 v[16:19], v[90:93], v[114:117], v[12:15]
	s_nop 6
	v_add_u32_e32 v12, 1, v56
	v_mfma_f32_16x16x32_bf16 v[66:69], v[98:101], v[86:89], v[66:69]
	v_mfma_f32_16x16x32_bf16 v[86:89], v[90:93], v[94:97], v[44:47]
	v_mfma_f32_16x16x32_bf16 v[44:47], v[90:93], v[106:109], v[40:43]
	v_mfma_f32_16x16x32_bf16 v[40:43], v[102:105], v[106:109], v[70:73]
	s_nop 2
	v_cvt_f32_i32_e32 v70, v12
	v_mfma_f32_16x16x32_bf16 v[12:15], v[102:105], v[114:117], v[66:69]
	s_nop 2
	v_mul_f32_e32 v66, v57, v70
	v_cmp_gt_f32_e32 vcc, s65, v66
	v_cndmask_b32_e64 v67, v167, v170, s[8:9]
	v_mfma_f32_16x16x32_bf16 v[94:97], v[102:105], v[94:97], v[24:27]
	v_cndmask_b32_e32 v66, 0, v78, vcc
	v_fmac_f32_e32 v66, v57, v70
	v_exp_f32_e32 v66, v66
	v_mfma_f32_16x16x32_bf16 v[24:27], v[102:105], v[110:113], v[74:77]
	s_nop 2
	v_lshlrev_b32_e32 v76, 2, v67
	v_cndmask_b32_e32 v67, 0, v80, vcc
	v_ldexp_f32 v68, v66, v67
	v_fma_f32 v81, v68, v86, v62
	v_add_f32_e32 v69, 0, v81
	v_mov_b32_e32 v66, v87
	v_mov_b32_e32 v67, v88
	v_mov_b32_e32 v62, v63
	v_mov_b32_e32 v63, v64
	v_pk_fma_f32 v[74:75], v[68:69], v[66:67], v[62:63] op_sel_hi:[0,1,1]
	v_add_f32_e32 v62, v74, v69
	v_add_f32_e32 v66, v75, v62
	v_pk_mul_f32 v[62:63], v[74:75], v[74:75]
	v_mov_b32_e32 v88, v94
	v_mov_b32_e32 v64, v58
	v_fma_f32 v62, v81, v81, v62
	v_pk_fma_f32 v[72:73], v[68:69], v[88:89], v[64:65] op_sel_hi:[0,1,1]
	v_add_f32_e32 v63, v63, v62
	v_mov_b32_e32 v69, v73
	v_mov_b32_e32 v64, v95
	v_mov_b32_e32 v65, v73
	v_mov_b32_e32 v62, v59
	v_pk_fma_f32 v[70:71], v[68:69], v[64:65], v[62:63]
	v_mul_f32_e32 v62, v72, v72
	v_pk_add_f32 v[62:63], v[70:71], v[62:63] op_sel_hi:[1,0]
	v_mul_f32_e32 v64, v70, v70
	v_pk_add_f32 v[62:63], v[64:65], v[62:63] op_sel_hi:[0,1]
	v_fma_f32 v69, v68, v96, v60
	v_add_f32_e32 v58, v73, v66
	v_mov_b32_e32 v64, v97
	v_mov_b32_e32 v65, v69
	v_mov_b32_e32 v62, v61
	v_add_f32_e32 v58, v72, v58
	v_mul_f32_e32 v71, v68, v97
	v_pk_fma_f32 v[66:67], v[68:69], v[64:65], v[62:63]
	v_mov_b32_e32 v59, v61
	v_pk_add_f32 v[58:59], v[58:59], v[70:71]
	v_pk_mov_b32 v[60:61], v[68:69], v[66:67] op_sel:[1,0]
	v_cmp_lt_i32_e32 vcc, v169, v168
	v_pk_add_f32 v[62:63], v[60:61], v[58:59]
	v_pk_mul_f32 v[58:59], v[60:61], v[58:59]
	v_mfma_f32_16x16x32_bf16 v[32:35], v[90:93], v[110:113], v[82:85]
	v_mov_b32_e32 v63, v59
	v_pk_add_f32 v[58:59], v[66:67], v[62:63]
	ds_bpermute_b32 v60, v76, v58
	ds_bpermute_b32 v61, v76, v59
	v_cndmask_b32_e32 v62, v167, v169, vcc
	v_lshlrev_b32_e32 v67, 2, v62
	v_cmp_eq_u32_e32 vcc, 0, v55
	v_lshl_add_u32 v55, v53, 3, 0
	s_waitcnt lgkmcnt(0)
	v_pk_add_f32 v[58:59], v[58:59], v[60:61]
	ds_bpermute_b32 v60, v67, v58
	ds_bpermute_b32 v61, v67, v59
	s_and_saveexec_b64 s[8:9], vcc
	s_cbranch_execz .LBB0_1724
	v_lshl_add_u32 v53, v56, 5, v55
	s_waitcnt lgkmcnt(0)
	v_pk_add_f32 v[58:59], v[58:59], v[60:61]
	ds_write_b64 v53, v[58:59]
